# comb5: pipelined P.V block + v_max3 row max in BOTH layers, on top of inverted prio + D!=C last QK MFMA + fold
# speedup vs baseline: 1.0116x; 1.0049x over previous
; #define LAS __attribute__((address_space(3)))
; __device__ __forceinline__ unsigned cvt_pk(float lo, float hi) { unsigned r; asm volatile("v_cvt_pk_bf16_f32 %0, %1, %2" : "=v"(r) : "v"(lo), "v"(hi)); return r; }
; __device__ __forceinline__ void attn_unit(LAS unsigned char* lds, int b, int h, int q0, int kbeg, int ntiles, const bf16_t* Q, const bf16_t* K, const bf16_t* Vt, bf16_t* cat) {
;     ...
;         const LAS unsigned char* kb = lds + (buf ^ 1) * AK_BYTES + r32 * (KP * 2) + hi * 16;
;         f32x16 pn0, pn1;
; #pragma unroll
;         for (int r = 0; r < 16; ++r) { pn0[r] = 0.f; pn1[r] = 0.f; }
;         float ps = 0.f; u32x4 pw[4];
;         bf16x8 ka = *(const LAS bf16x8*)(kb), kbb = *(const LAS bf16x8*)(kb + 32 * (KP * 2));
; #pragma unroll
;         for (int ds = 0; ds < 12; ++ds) {
;             bf16x8 na = ka, nb = kbb;
;             if (ds < 11) { na = *(const LAS bf16x8*)(kb + (ds + 1) * 32); nb = *(const LAS bf16x8*)(kb + 32 * (KP * 2) + (ds + 1) * 32); }
;             pn0 = __builtin_amdgcn_mfma_f32_32x32x16_bf16(ka, qf[ds], pn0, 0, 0, 0);
;             pn1 = __builtin_amdgcn_mfma_f32_32x32x16_bf16(kbb, qf[ds], pn1, 0, 0, 0);
;             if (ds < 8) {
;                 float e[4];
; #pragma unroll
;                 for (int j = 0; j < 4; ++j) { const float v = ds < 4 ? pc0[4 * ds + j] : pc1[4 * (ds - 4) + j]; e[j] = __builtin_amdgcn_exp2f(v - mrun); }
;                 ps += (e[0] + e[1]) + (e[2] + e[3]);
;                 const unsigned w0 = cvt_pk(e[0], e[1]), w1 = cvt_pk(e[2], e[3]);
;                 if ((ds & 1) == 0) { pw[ds >> 1].x = w0; pw[ds >> 1].y = w1; } else { pw[ds >> 1].z = w0; pw[ds >> 1].w = w1; }
;             }
;             ka = na; kbb = nb;
;             __builtin_amdgcn_sched_barrier(0);
;         }
.LBB0_814:
	s_xor_b32 s6, s5, 1
	s_mul_i32 s7, s6, 0x6400
	v_add_u32_e32 v236, s7, v228
	ds_read_b128 v[98:101], v236
	v_sub_f32_e32 v82, v82, v230
	v_exp_f32_e32 v197, v82
	v_sub_f32_e32 v82, v84, v230
	v_exp_f32_e32 v201, v82
	v_sub_f32_e32 v82, v85, v230
	v_exp_f32_e32 v233, v82
	v_sub_f32_e32 v82, v86, v230
	v_exp_f32_e32 v196, v82
	v_sub_f32_e32 v82, v87, v230
	s_waitcnt lgkmcnt(0)
	v_mfma_f32_32x32x16_bf16 v[98:113], v[98:101], v[174:177], 0
	v_exp_f32_e32 v198, v82
	v_sub_f32_e32 v82, v88, v230
	v_sub_f32_e32 v83, v83, v230
	v_exp_f32_e32 v200, v82
	v_sub_f32_e32 v82, v89, v230
	v_exp_f32_e32 v199, v83
	v_exp_f32_e32 v232, v82
	ds_read_b128 v[188:191], v236 offset:32
	ds_read_b128 v[114:117], v236 offset:12800
	ds_read_b128 v[192:195], v236 offset:12832
	s_add_i32 s4, s4, 1
	v_pk_add_f32 v[82:83], v[196:197], v[198:199]
	v_pk_add_f32 v[84:85], v[200:201], v[232:233]
	s_waitcnt lgkmcnt(0)
	v_mfma_f32_32x32x16_bf16 v[114:129], v[114:117], v[174:177], 0
	v_add_f32_e64 v234, v82, v84
	v_add_f32_e64 v235, v83, v85
	v_cvt_pk_bf16_f32 v186, v197, v199
	v_cvt_pk_bf16_f32 v187, v201, v233
	v_add_f32_e32 v235, 0, v235
	v_mfma_f32_32x32x16_bf16 v[98:113], v[188:191], v[170:173], v[98:113]
	ds_read_b128 v[82:85], v236 offset:64
	ds_read_b128 v[86:89], v236 offset:12864
	v_add_f32_e32 v197, v234, v235
	v_cvt_pk_bf16_f32 v188, v196, v198
	v_cvt_pk_bf16_f32 v189, v200, v232
	v_mfma_f32_32x32x16_bf16 v[114:129], v[192:195], v[170:173], v[114:129]
	v_sub_f32_e32 v90, v90, v230
	s_waitcnt lgkmcnt(0)
	v_mfma_f32_32x32x16_bf16 v[98:113], v[82:85], v[166:169], v[98:113]
	v_exp_f32_e32 v190, v90
	v_sub_f32_e32 v90, v91, v230
	v_exp_f32_e32 v192, v90
	v_sub_f32_e32 v90, v92, v230
	v_sub_f32_e32 v82, v93, v230
	v_exp_f32_e32 v191, v90
	v_exp_f32_e32 v193, v82
	ds_read_b128 v[82:85], v236 offset:96
	ds_read_b128 v[90:93], v236 offset:12896
	v_mfma_f32_32x32x16_bf16 v[114:129], v[86:89], v[166:169], v[114:129]
	v_add_f32_e64 v194, v190, v192
	v_add_f32_e64 v195, v191, v193
	v_add_f32_e64 v198, v194, v194
	v_add_f32_e64 v199, v194, v195
	v_cvt_pk_bf16_f32 v190, v190, v192
	v_cvt_pk_bf16_f32 v191, v191, v193
	v_sub_f32_e32 v86, v94, v230
	s_waitcnt lgkmcnt(0)
	v_mfma_f32_32x32x16_bf16 v[98:113], v[82:85], v[162:165], v[98:113]
	v_exp_f32_e32 v94, v86
	v_sub_f32_e32 v86, v95, v230
	v_exp_f32_e32 v192, v86
	v_sub_f32_e32 v86, v96, v230
	v_sub_f32_e32 v82, v97, v230
	v_exp_f32_e32 v96, v86
	v_exp_f32_e32 v193, v82
	ds_read_b128 v[82:85], v236 offset:128
	ds_read_b128 v[86:89], v236 offset:12928
	v_add_f32_e32 v95, v94, v192
	v_cvt_pk_bf16_f32 v192, v94, v192
	v_add_f32_e32 v97, v96, v193
	v_mfma_f32_32x32x16_bf16 v[114:129], v[90:93], v[162:165], v[114:129]
	v_cvt_pk_bf16_f32 v193, v96, v193
	v_sub_f32_e32 v66, v66, v230
	v_exp_f32_e32 v94, v66
	v_sub_f32_e32 v66, v67, v230
	v_exp_f32_e32 v96, v66
	v_sub_f32_e32 v66, v68, v230
	v_exp_f32_e32 v198, v66
	s_waitcnt lgkmcnt(0)
	v_mfma_f32_32x32x16_bf16 v[98:113], v[82:85], v[158:161], v[98:113]
	v_sub_f32_e32 v66, v69, v230
	v_exp_f32_e32 v196, v66
	ds_read_b128 v[66:69], v236 offset:160
	ds_read_b128 v[82:85], v236 offset:12960
	v_pk_add_f32 v[90:91], v[94:95], v[96:97]
	v_cvt_pk_bf16_f32 v194, v94, v96
	v_pk_add_f32 v[92:93], v[198:199], v[196:197]
	v_cvt_pk_bf16_f32 v195, v198, v196
	v_mfma_f32_32x32x16_bf16 v[114:129], v[86:89], v[158:161], v[114:129]
	v_add_f32_e64 v90, v90, v92
	v_add_f32_e64 v91, v91, v93
	v_add_f32_e64 v86, v90, v90
	v_add_f32_e64 v87, v90, v91
	v_sub_f32_e32 v70, v70, v230
	v_exp_f32_e32 v88, v70
	v_sub_f32_e32 v70, v71, v230
	s_waitcnt lgkmcnt(0)
	v_mfma_f32_32x32x16_bf16 v[98:113], v[66:69], v[154:157], v[98:113]
	v_exp_f32_e32 v90, v70
	v_sub_f32_e32 v70, v72, v230
	v_sub_f32_e32 v66, v73, v230
	v_exp_f32_e32 v89, v70
	v_exp_f32_e32 v91, v66
	ds_read_b128 v[66:69], v236 offset:192
	ds_read_b128 v[70:73], v236 offset:12992
	v_cvt_pk_bf16_f32 v196, v88, v90
	v_mfma_f32_32x32x16_bf16 v[114:129], v[82:85], v[154:157], v[114:129]
	v_add_f32_e64 v92, v88, v90
	v_add_f32_e64 v93, v89, v91
	v_cvt_pk_bf16_f32 v197, v89, v91
	v_pk_add_f32 v[92:93], v[92:93], v[92:93] op_sel_hi:[0,1]
	v_sub_f32_e32 v74, v74, v230
	s_waitcnt lgkmcnt(0)
	v_mfma_f32_32x32x16_bf16 v[98:113], v[66:69], v[150:153], v[98:113]
	v_exp_f32_e32 v82, v74
	v_sub_f32_e32 v74, v75, v230
	v_exp_f32_e32 v84, v74
	v_sub_f32_e32 v74, v76, v230
	v_sub_f32_e32 v66, v77, v230
	v_exp_f32_e32 v86, v74
	v_exp_f32_e32 v88, v66
	ds_read_b128 v[66:69], v236 offset:224
	ds_read_b128 v[74:77], v236 offset:13024
	v_add_f32_e32 v83, v82, v84
	v_cvt_pk_bf16_f32 v198, v82, v84
	v_add_f32_e32 v85, v86, v88
	v_mfma_f32_32x32x16_bf16 v[114:129], v[70:73], v[150:153], v[114:129]
	v_cvt_pk_bf16_f32 v199, v86, v88
	v_sub_f32_e32 v70, v78, v230
	v_exp_f32_e32 v82, v70
	v_sub_f32_e32 v70, v79, v230
	s_waitcnt lgkmcnt(0)
; #define LAS __attribute__((address_space(3)))
; #define ASTOREV(buf) do { LAS unsigned char* vd_ = lds + 2 * AK_BYTES + (buf) * AV_BYTES + vd0 * AV_PITCH + vpart * 16; \
;         *(LAS u32x2*)(vd_) = (u32x2){vr[0].x, vr[0].y}; *(LAS u32x2*)(vd_ + 8) = (u32x2){vr[0].z, vr[0].w}; \
;         *(LAS u32x2*)(vd_ + 64 * AV_PITCH) = (u32x2){vr[1].x, vr[1].y}; *(LAS u32x2*)(vd_ + 64 * AV_PITCH + 8) = (u32x2){vr[1].z, vr[1].w}; } while (0)
; __device__ __forceinline__ void attn_unit(LAS unsigned char* lds, int b, int h, int q0, int kbeg, int ntiles, const bf16_t* Q, const bf16_t* K, const bf16_t* Vt, bf16_t* cat) {
;     ...
;         lrun += ps;
;         const LAS unsigned char* vb = lds + 2 * AK_BYTES + buf * AV_BYTES + r32 * AV_PITCH + hi * 8;
; #pragma unroll
;         for (int d = 0; d < 4; ++d)
; #pragma unroll
;             for (int ks = 0; ks < 4; ++ks) {
;                 const s16x4 lo = *(const LAS s16x4*)(vb + d * 32 * AV_PITCH + ks * 32), hh = *(const LAS s16x4*)(vb + d * 32 * AV_PITCH + ks * 32 + 16);
;                 const bf16x8 vf = (bf16x8){lo[0], lo[1], lo[2], lo[3], hh[0], hh[1], hh[2], hh[3]};
;                 o[d] = __builtin_amdgcn_mfma_f32_32x32x16_bf16(vf, __builtin_bit_cast(bf16x8, pw[ks]), o[d], 0, 0, 0);
;             }
;         { float mx = fmaxf(pn0[0], pn1[0]);
; #pragma unroll
;           for (int r = 1; r < 16; ++r) mx = fmaxf(mx, fmaxf(pn0[r], pn1[r]));
;           mxc = fmaxf(mx, __shfl_xor(mx, 32)); }
;         if (kt + 1 < ntiles) ASTOREV(buf ^ 1);
;         asm volatile("s_waitcnt vmcnt(0)" ::: "memory");
;         __syncthreads();
;         pc0 = pn0; pc1 = pn1;
	v_mfma_f32_32x32x16_bf16 v[98:113], v[66:69], v[146:149], v[98:113]
	v_exp_f32_e32 v84, v70
	v_sub_f32_e32 v70, v80, v230
	v_sub_f32_e32 v66, v81, v230
	v_exp_f32_e32 v92, v70
	v_exp_f32_e32 v86, v66
	ds_read_b128 v[66:69], v236 offset:256
	ds_read_b128 v[70:73], v236 offset:13056
	v_pk_add_f32 v[78:79], v[82:83], v[84:85]
	v_mfma_f32_32x32x16_bf16 v[114:129], v[74:77], v[146:149], v[114:129]
	v_add_f32_e64 v80, v92, v86
	v_add_f32_e64 v81, v93, v87
	v_cvt_pk_bf16_f32 v200, v82, v84
	v_cvt_pk_bf16_f32 v201, v92, v86
	v_add_f32_e64 v78, v78, v80
	v_add_f32_e64 v79, v79, v81
	v_add_f32_e32 v237, v78, v79
	s_waitcnt lgkmcnt(0)
	v_mfma_f32_32x32x16_bf16 v[98:113], v[66:69], v[142:145], v[98:113]
	ds_read_b128 v[66:69], v236 offset:288
	ds_read_b128 v[74:77], v236 offset:13088
	v_mfma_f32_32x32x16_bf16 v[114:129], v[70:73], v[142:145], v[114:129]
	s_waitcnt lgkmcnt(0)
	v_mfma_f32_32x32x16_bf16 v[98:113], v[66:69], v[138:141], v[98:113]
	ds_read_b128 v[66:69], v236 offset:320
	ds_read_b128 v[70:73], v236 offset:13120
	v_mfma_f32_32x32x16_bf16 v[114:129], v[74:77], v[138:141], v[114:129]
	s_waitcnt lgkmcnt(0)
	v_mfma_f32_32x32x16_bf16 v[98:113], v[66:69], v[134:137], v[98:113]
	ds_read_b128 v[66:69], v236 offset:352
	ds_read_b128 v[232:235], v236 offset:13152
	v_mfma_f32_32x32x16_bf16 v[114:129], v[70:73], v[134:137], v[114:129]
	s_waitcnt lgkmcnt(0)
	v_mfma_f32_32x32x16_bf16 v[82:97], v[66:69], v[130:133], v[98:113]
	v_mfma_f32_32x32x16_bf16 v[66:81], v[232:235], v[130:133], v[114:129]
	s_mulk_i32 s5, 0x4400
	v_add_u32_e32 v232, s5, v229
	v_add_u32_e32 v250, 0xc800, v232
	v_add_u32_e32 v251, 0xd800, v232
	v_add_u32_e32 v252, 0xe800, v232
	v_add_u32_e32 v253, 0xf800, v232
	s_mulk_i32 s6, 0x4400
	ds_read2_b64 v[98:101], v250 offset1:2
	ds_read2_b64 v[102:105], v251 offset0:32 offset1:34
	ds_read2_b64 v[106:109], v252 offset0:64 offset1:66
	ds_read2_b64 v[110:113], v253 offset0:96 offset1:98
	ds_read2_b64 v[114:117], v250 offset0:4 offset1:6
	ds_read2_b64 v[118:121], v251 offset0:36 offset1:38
	ds_read2_b64 v[122:125], v252 offset0:68 offset1:70
	ds_read2_b64 v[126:129], v253 offset0:100 offset1:102
	v_add_f32_e32 v202, v202, v237
	v_max3_f32 v254, v82, v66, v83
	v_max3_f32 v254, v254, v67, v84
	v_max3_f32 v254, v254, v68, v85
	v_max3_f32 v254, v254, v69, v86
	s_waitcnt lgkmcnt(7)
	v_mfma_f32_32x32x16_bf16 v[50:65], v[98:101], v[186:189], v[50:65]
	ds_read2_b64 v[98:101], v250 offset0:8 offset1:10
	v_max3_f32 v254, v254, v70, v87
	v_max3_f32 v254, v254, v71, v88
	s_waitcnt lgkmcnt(7)
	v_mfma_f32_32x32x16_bf16 v[34:49], v[102:105], v[186:189], v[34:49]
	ds_read2_b64 v[102:105], v251 offset0:40 offset1:42
	v_max3_f32 v254, v254, v72, v89
	v_max3_f32 v254, v254, v73, v90
	s_waitcnt lgkmcnt(7)
	v_mfma_f32_32x32x16_bf16 v[18:33], v[106:109], v[186:189], v[18:33]
	ds_read2_b64 v[106:109], v252 offset0:72 offset1:74
	v_max3_f32 v254, v254, v74, v91
	v_max3_f32 v254, v254, v75, v92
	s_waitcnt lgkmcnt(7)
	v_mfma_f32_32x32x16_bf16 v[2:17], v[110:113], v[186:189], v[2:17]
	ds_read2_b64 v[110:113], v253 offset0:104 offset1:106
	v_max3_f32 v254, v254, v76, v93
	v_max3_f32 v254, v254, v77, v94
	s_waitcnt lgkmcnt(7)
	v_mfma_f32_32x32x16_bf16 v[50:65], v[114:117], v[190:193], v[50:65]
	ds_read2_b64 v[114:117], v250 offset0:12 offset1:14
	v_max3_f32 v254, v254, v78, v95
	v_max3_f32 v254, v254, v79, v96
	s_waitcnt lgkmcnt(7)
	v_mfma_f32_32x32x16_bf16 v[34:49], v[118:121], v[190:193], v[34:49]
	ds_read2_b64 v[118:121], v251 offset0:44 offset1:46
	v_max3_f32 v254, v254, v80, v97
	v_max_f32_e32 v254, v254, v81
	s_waitcnt lgkmcnt(7)
	v_mfma_f32_32x32x16_bf16 v[18:33], v[122:125], v[190:193], v[18:33]
	ds_read2_b64 v[122:125], v252 offset0:76 offset1:78
	v_lshl_add_u64 v[212:213], v[212:213], 0, s[60:61]
	v_lshl_add_u64 v[214:215], v[214:215], 0, s[60:61]
	s_waitcnt lgkmcnt(7)
	v_mfma_f32_32x32x16_bf16 v[2:17], v[126:129], v[190:193], v[2:17]
	ds_read2_b64 v[126:129], v253 offset0:108 offset1:110
	v_lshl_add_u64 v[216:217], v[216:217], 0, s[60:61]
	v_lshl_add_u64 v[218:219], v[218:219], 0, s[60:61]
	v_lshl_add_u64 v[220:221], v[220:221], 0, s[66:67]
	ds_bpermute_b32 v255, v207, v254
	s_waitcnt lgkmcnt(8)
	v_mfma_f32_32x32x16_bf16 v[50:65], v[98:101], v[194:197], v[50:65]
	s_waitcnt lgkmcnt(7)
	v_mfma_f32_32x32x16_bf16 v[34:49], v[102:105], v[194:197], v[34:49]
	s_waitcnt lgkmcnt(6)
	v_mfma_f32_32x32x16_bf16 v[18:33], v[106:109], v[194:197], v[18:33]
	s_waitcnt lgkmcnt(5)
	v_mfma_f32_32x32x16_bf16 v[2:17], v[110:113], v[194:197], v[2:17]
	s_waitcnt lgkmcnt(0)
	v_max_f32_e32 v255, v255, v255
	v_max_f32_e32 v98, v254, v255
	v_add_u32_e32 v255, s6, v231
	v_add_u32_e32 v238, 0xc800, v255
	v_add_u32_e32 v255, 0xea00, v255
	s_cmp_lg_u32 s4, 34
	s_waitcnt vmcnt(0)
	ds_write2_b64 v238, v[178:179], v[180:181] offset1:1
	ds_write2_b64 v255, v[182:183], v[184:185] offset1:1
	s_waitcnt vmcnt(0)
	s_waitcnt lgkmcnt(0)
	s_barrier
	v_mfma_f32_32x32x16_bf16 v[50:65], v[114:117], v[198:201], v[50:65]
	v_mfma_f32_32x32x16_bf16 v[34:49], v[118:121], v[198:201], v[34:49]
	v_mfma_f32_32x32x16_bf16 v[18:33], v[122:125], v[198:201], v[18:33]
	v_mfma_f32_32x32x16_bf16 v[2:17], v[126:129], v[198:201], v[2:17]
	s_cbranch_scc0 .LBB0_819
